# gdn_pre: off-diagonal blocks of (I+A)^-1 via v_mfma_f32_16x16x4_f32 (f32 in, f32 acc) instead of scalar LDS reads + FMAs
# speedup vs baseline: 1.7177x; 1.0151x over previous
; __device__ __forceinline__ void gdn_pre_phase(const Args& a, LAS unsigned char* lds, int slot) {
;     ...
;         {
;             G1_LANEVARS
;             const int base = quad * 16, cc = r;
;             for (int i = 1; i < 16; ++i) {
;                 float tacc = 0.f;
;                 for (int j = 0; j < i; ++j) {
;                     const float aij = AT[(base + i) * 65 + base + j];
;                     const float tj = (j > cc) ? AT[(base + j) * 65 + base + cc] : (j == cc ? 1.f : 0.f);
;                     tacc -= aij * tj;
;                 }
;                 asm volatile("s_waitcnt lgkmcnt(0)" ::: "memory");
;                 if (cc < i) AT[(base + i) * 65 + base + cc] = tacc;
;                 asm volatile("s_waitcnt lgkmcnt(0)" ::: "memory");
;             }
; #pragma unroll 1
;             for (int lev = 1; lev < 4; ++lev)
; #pragma unroll 1
;                 for (int bb = 0; bb < 4 - lev; ++bb) {
;                     const int aa = bb + lev, q4 = quad * 4;
;                     float mv[4] = {0.f, 0.f, 0.f, 0.f};
;                     for (int cb = bb; cb < aa; ++cb) {
;                         for (int k = 0; k < 16; ++k) {
;                             float tk;
;                             if (cb == bb) tk = (cc < k) ? AT[(bb * 16 + k) * 65 + bb * 16 + cc] : (cc == k ? 1.f : 0.f);
;                             else tk = AT[(bb * 16 + k) * 65 + cb * 16 + cc];
; #pragma unroll
;                             for (int jj = 0; jj < 4; ++jj) mv[jj] += AT[(aa * 16 + q4 + jj) * 65 + cb * 16 + k] * tk;
;                         }
;                     }
;                     asm volatile("s_waitcnt lgkmcnt(0)" ::: "memory");
; #pragma unroll
;                     for (int jj = 0; jj < 4; ++jj) AT[(bb * 16 + q4 + jj) * 65 + aa * 16 + cc] = mv[jj];
;                     asm volatile("s_waitcnt lgkmcnt(0)" ::: "memory");
;                     float tv[4] = {mv[0], mv[1], mv[2], mv[3]};
;                     for (int k = 0; k < 16; ++k) {
;                         const float mk = AT[(bb * 16 + k) * 65 + aa * 16 + cc];
; #pragma unroll
;                         for (int jj = 0; jj < 4; ++jj) { const int ii = q4 + jj; const float dv = AT[(aa * 16 + ii) * 65 + aa * 16 + k]; if (k < ii) tv[jj] += dv * mk; }
;                     }
;                     asm volatile("s_waitcnt lgkmcnt(0)" ::: "memory");
; #pragma unroll
.LBB0_2071:
	s_or_b64 exec, exec, s[0:1]
	v_cmp_eq_u32_e32 vcc, 1, v0
	v_readlane_b32 s38, v255, 13
	v_readlane_b32 s39, v255, 14
	v_cndmask_b32_e64 v63, 0, 1.0, vcc
	v_cmp_eq_u32_e32 vcc, 2, v0
	s_waitcnt lgkmcnt(13)
	v_lshlrev_b32_e32 v2, 2, v0
	v_ashrrev_i32_e32 v3, 2, v4
	v_cndmask_b32_e64 v69, 0, 1.0, vcc
	v_cmp_eq_u32_e32 vcc, 3, v0
	s_waitcnt lgkmcnt(9)
	v_cndmask_b32_e64 v18, 0, 1.0, s[38:39]
	v_readlane_b32 s38, v255, 3
	v_cndmask_b32_e64 v75, 0, 1.0, vcc
	v_cmp_eq_u32_e32 vcc, 4, v0
	s_waitcnt lgkmcnt(0)
	v_and_b32_e32 v39, -4, v3
	v_add_u32_e32 v105, s38, v2
	v_cndmask_b32_e64 v81, 0, 1.0, vcc
	v_cmp_eq_u32_e32 vcc, 5, v0
	s_movk_i32 s38, 0x410
	v_or_b32_e32 v51, 2, v39
	v_cndmask_b32_e64 v87, 0, 1.0, vcc
	v_cmp_eq_u32_e32 vcc, 6, v0
	v_or_b32_e32 v57, 3, v3
	s_waitcnt lgkmcnt(1)
	v_add_u32_e32 v33, s49, v2
	v_cndmask_b32_e64 v96, 0, 1.0, vcc
	v_cmp_eq_u32_e32 vcc, 7, v0
	s_mov_b32 s33, 3
	v_cmp_lt_i32_e64 s[66:67], 3, v3
	v_cndmask_b32_e64 v97, 0, 1.0, vcc
	v_cmp_eq_u32_e32 vcc, 8, v0
	s_mov_b32 s42, 1
	v_or_b32_e32 v45, 1, v39
	v_cndmask_b32_e64 v98, 0, 1.0, vcc
	v_cmp_eq_u32_e32 vcc, 9, v0
	v_cmp_lt_i32_e64 s[68:69], -1, v3
	v_cmp_lt_i32_e64 s[70:71], 3, v51
	v_cndmask_b32_e64 v99, 0, 1.0, vcc
	v_cmp_eq_u32_e32 vcc, 10, v0
	v_cmp_lt_i32_e64 s[72:73], 3, v57
	v_cmp_lt_i32_e64 s[74:75], 4, v39
	v_cndmask_b32_e64 v100, 0, 1.0, vcc
	v_cmp_eq_u32_e32 vcc, 11, v0
	v_cmp_lt_i32_e64 s[76:77], 4, v57
	v_cmp_lt_i32_e64 s[78:79], 5, v39
	v_cndmask_b32_e64 v101, 0, 1.0, vcc
	v_cmp_eq_u32_e32 vcc, 12, v0
	v_cmp_lt_i32_e64 s[80:81], 5, v51
	v_cmp_lt_i32_e64 s[82:83], 5, v57
	v_cndmask_b32_e64 v102, 0, 1.0, vcc
	v_cmp_eq_u32_e32 vcc, 13, v0
	v_cmp_lt_i32_e64 s[84:85], 6, v39
	v_cmp_lt_i32_e64 s[86:87], 6, v57
	v_cndmask_b32_e64 v103, 0, 1.0, vcc
	v_cmp_eq_u32_e32 vcc, 14, v0
	v_lshrrev_b32_e32 v0, 2, v3
	v_mul_lo_u32 v0, v0, s38
	v_readlane_b32 s38, v255, 4
	v_cmp_lt_i32_e64 s[88:89], 7, v39
	v_cmp_lt_i32_e64 s[90:91], 7, v51
	v_cmp_lt_i32_e64 s[92:93], 7, v57
	v_cmp_lt_i32_e64 s[94:95], 8, v39
	v_cmp_lt_i32_e64 s[96:97], 8, v57
	v_cmp_lt_i32_e64 s[2:3], 9, v39
	v_cmp_lt_i32_e64 s[4:5], 9, v51
	v_cmp_lt_i32_e64 s[6:7], 9, v57
	v_cmp_lt_i32_e64 s[8:9], 10, v39
	v_cmp_lt_i32_e64 s[10:11], 10, v57
	v_cmp_lt_i32_e64 s[12:13], 11, v39
	v_cmp_lt_i32_e64 s[14:15], 11, v51
	v_cmp_lt_i32_e64 s[16:17], 11, v57
	v_cmp_lt_i32_e64 s[18:19], 12, v39
	v_cmp_lt_i32_e64 s[20:21], 12, v57
	v_cmp_lt_i32_e64 s[22:23], 13, v39
	v_cmp_lt_i32_e64 s[24:25], 13, v51
	v_cmp_lt_i32_e64 s[26:27], 13, v57
	v_cmp_lt_i32_e64 s[28:29], 14, v39
	v_cmp_lt_i32_e64 s[30:31], 14, v57
	v_cmp_lt_i32_e64 s[34:35], 15, v39
	v_cmp_lt_i32_e64 s[0:1], 15, v51
	v_cmp_lt_i32_e64 s[36:37], 15, v57
	v_cndmask_b32_e64 v104, 0, 1.0, vcc
	v_mov_b32_e32 v19, v18
	v_add_u32_e32 v106, s38, v0
	s_mov_b64 exec, -1
	v_and_b32_e32 v0, 15, v174
	v_lshrrev_b32_e32 v9, 4, v174
	v_mul_u32_u24_e32 v2, 0x41, v0
	v_mul_u32_u24_e32 v3, 0x41, v9
	v_mul_u32_u24_e32 v4, 0x104, v9
	v_add_u32_e32 v2, v2, v9
	v_add_u32_e32 v3, v3, v0
	v_add_u32_e32 v4, v4, v0
	v_lshl_add_u32 v2, v2, 2, s49
	v_lshl_add_u32 v3, v3, 2, s49
	v_lshl_add_u32 v4, v4, 2, s49
	v_sub_u32_e32 v0, v0, v9
	v_cmp_eq_u32_e32 vcc, 0, v0
	s_nop 1
	v_cndmask_b32_e64 v5, 0, 1.0, vcc
	v_cmp_eq_u32_e32 vcc, 4, v0
	s_nop 1
	v_cndmask_b32_e64 v6, 0, 1.0, vcc
	v_cmp_eq_u32_e32 vcc, 8, v0
	s_nop 1
	v_cndmask_b32_e64 v7, 0, 1.0, vcc
	v_cmp_eq_u32_e32 vcc, 12, v0
	s_nop 1
	v_cndmask_b32_e64 v8, 0, 1.0, vcc
	ds_read_b32 v10, v2 offset:4160
	ds_read_b32 v11, v2 offset:4176
	ds_read_b32 v12, v2 offset:4192
	ds_read_b32 v13, v2 offset:4208
	ds_read_b32 v14, v3 offset:0
	ds_read_b32 v15, v3 offset:1040
	ds_read_b32 v16, v3 offset:2080
	ds_read_b32 v17, v3 offset:3120
	s_waitcnt lgkmcnt(0)
	v_add_f32_e32 v14, v14, v5
	v_add_f32_e32 v15, v15, v6
	v_add_f32_e32 v16, v16, v7
	v_add_f32_e32 v17, v17, v8
	s_nop 1
	v_mfma_f32_16x16x4_f32 v[28:31], v10, v14, 0
	v_mfma_f32_16x16x4_f32 v[28:31], v11, v15, v[28:31]
	v_mfma_f32_16x16x4_f32 v[28:31], v12, v16, v[28:31]
	v_mfma_f32_16x16x4_f32 v[28:31], v13, v17, v[28:31]
	s_nop 9
	ds_write_b32 v4, v28 offset:64
	ds_write_b32 v4, v29 offset:324
	ds_write_b32 v4, v30 offset:584
	ds_write_b32 v4, v31 offset:844
	ds_read_b32 v10, v2 offset:4224
	ds_read_b32 v11, v2 offset:4240
	ds_read_b32 v12, v2 offset:4256
	ds_read_b32 v13, v2 offset:4272
	ds_read_b32 v14, v3 offset:64
	ds_read_b32 v15, v3 offset:1104
	ds_read_b32 v16, v3 offset:2144
	ds_read_b32 v17, v3 offset:3184
	s_waitcnt lgkmcnt(0)
	v_mfma_f32_16x16x4_f32 v[28:31], v10, v14, v[28:31]
	v_mfma_f32_16x16x4_f32 v[28:31], v11, v15, v[28:31]
	v_mfma_f32_16x16x4_f32 v[28:31], v12, v16, v[28:31]
	v_mfma_f32_16x16x4_f32 v[28:31], v13, v17, v[28:31]
	s_nop 9
	v_xor_b32_e32 v28, 0x80000000, v28
	v_xor_b32_e32 v29, 0x80000000, v29
	v_xor_b32_e32 v30, 0x80000000, v30
	v_xor_b32_e32 v31, 0x80000000, v31
	ds_write_b32 v4, v28 offset:64
	ds_write_b32 v4, v29 offset:324
	ds_write_b32 v4, v30 offset:584
	ds_write_b32 v4, v31 offset:844
	ds_read_b32 v10, v2 offset:8384
	ds_read_b32 v11, v2 offset:8400
	ds_read_b32 v12, v2 offset:8416
	ds_read_b32 v13, v2 offset:8432
	ds_read_b32 v14, v3 offset:4224
	ds_read_b32 v15, v3 offset:5264
	ds_read_b32 v16, v3 offset:6304
	ds_read_b32 v17, v3 offset:7344
	s_waitcnt lgkmcnt(0)
; __device__ __forceinline__ void gdn_pre_phase(const Args& a, LAS unsigned char* lds, int slot) {
;     ...
; #pragma unroll 1
;             for (int lev = 1; lev < 4; ++lev)
; #pragma unroll 1
;                 for (int bb = 0; bb < 4 - lev; ++bb) {
;                     const int aa = bb + lev, q4 = quad * 4;
;                     float mv[4] = {0.f, 0.f, 0.f, 0.f};
;                     for (int cb = bb; cb < aa; ++cb) {
;                         for (int k = 0; k < 16; ++k) {
;                             float tk;
;                             if (cb == bb) tk = (cc < k) ? AT[(bb * 16 + k) * 65 + bb * 16 + cc] : (cc == k ? 1.f : 0.f);
;                             else tk = AT[(bb * 16 + k) * 65 + cb * 16 + cc];
; #pragma unroll
;                             for (int jj = 0; jj < 4; ++jj) mv[jj] += AT[(aa * 16 + q4 + jj) * 65 + cb * 16 + k] * tk;
;                         }
;                     }
;                     asm volatile("s_waitcnt lgkmcnt(0)" ::: "memory");
; #pragma unroll
;                     for (int jj = 0; jj < 4; ++jj) AT[(bb * 16 + q4 + jj) * 65 + aa * 16 + cc] = mv[jj];
;                     asm volatile("s_waitcnt lgkmcnt(0)" ::: "memory");
;                     float tv[4] = {mv[0], mv[1], mv[2], mv[3]};
;                     for (int k = 0; k < 16; ++k) {
;                         const float mk = AT[(bb * 16 + k) * 65 + aa * 16 + cc];
; #pragma unroll
;                         for (int jj = 0; jj < 4; ++jj) { const int ii = q4 + jj; const float dv = AT[(aa * 16 + ii) * 65 + aa * 16 + k]; if (k < ii) tv[jj] += dv * mk; }
;                     }
;                     asm volatile("s_waitcnt lgkmcnt(0)" ::: "memory");
; #pragma unroll
;                     for (int jj = 0; jj < 4; ++jj) AT[(bb * 16 + q4 + jj) * 65 + aa * 16 + cc] = -tv[jj];
;                     asm volatile("s_waitcnt lgkmcnt(0)" ::: "memory");
;                 }
	v_add_f32_e32 v14, v14, v5
	v_add_f32_e32 v15, v15, v6
	v_add_f32_e32 v16, v16, v7
	v_add_f32_e32 v17, v17, v8
	s_nop 1
	v_mfma_f32_16x16x4_f32 v[28:31], v10, v14, 0
	v_mfma_f32_16x16x4_f32 v[28:31], v11, v15, v[28:31]
	v_mfma_f32_16x16x4_f32 v[28:31], v12, v16, v[28:31]
	v_mfma_f32_16x16x4_f32 v[28:31], v13, v17, v[28:31]
	s_nop 9
	ds_write_b32 v4, v28 offset:4288
	ds_write_b32 v4, v29 offset:4548
	ds_write_b32 v4, v30 offset:4808
	ds_write_b32 v4, v31 offset:5068
	ds_read_b32 v10, v2 offset:8448
	ds_read_b32 v11, v2 offset:8464
	ds_read_b32 v12, v2 offset:8480
	ds_read_b32 v13, v2 offset:8496
	ds_read_b32 v14, v3 offset:4288
	ds_read_b32 v15, v3 offset:5328
	ds_read_b32 v16, v3 offset:6368
	ds_read_b32 v17, v3 offset:7408
	s_waitcnt lgkmcnt(0)
	v_mfma_f32_16x16x4_f32 v[28:31], v10, v14, v[28:31]
	v_mfma_f32_16x16x4_f32 v[28:31], v11, v15, v[28:31]
	v_mfma_f32_16x16x4_f32 v[28:31], v12, v16, v[28:31]
	v_mfma_f32_16x16x4_f32 v[28:31], v13, v17, v[28:31]
	s_nop 9
	v_xor_b32_e32 v28, 0x80000000, v28
	v_xor_b32_e32 v29, 0x80000000, v29
	v_xor_b32_e32 v30, 0x80000000, v30
	v_xor_b32_e32 v31, 0x80000000, v31
	ds_write_b32 v4, v28 offset:4288
	ds_write_b32 v4, v29 offset:4548
	ds_write_b32 v4, v30 offset:4808
	ds_write_b32 v4, v31 offset:5068
	ds_read_b32 v10, v2 offset:12608
	ds_read_b32 v11, v2 offset:12624
	ds_read_b32 v12, v2 offset:12640
	ds_read_b32 v13, v2 offset:12656
	ds_read_b32 v14, v3 offset:8448
	ds_read_b32 v15, v3 offset:9488
	ds_read_b32 v16, v3 offset:10528
	ds_read_b32 v17, v3 offset:11568
	s_waitcnt lgkmcnt(0)
	v_add_f32_e32 v14, v14, v5
	v_add_f32_e32 v15, v15, v6
	v_add_f32_e32 v16, v16, v7
	v_add_f32_e32 v17, v17, v8
	s_nop 1
	v_mfma_f32_16x16x4_f32 v[28:31], v10, v14, 0
	v_mfma_f32_16x16x4_f32 v[28:31], v11, v15, v[28:31]
	v_mfma_f32_16x16x4_f32 v[28:31], v12, v16, v[28:31]
	v_mfma_f32_16x16x4_f32 v[28:31], v13, v17, v[28:31]
	s_nop 9
	ds_write_b32 v4, v28 offset:8512
	ds_write_b32 v4, v29 offset:8772
	ds_write_b32 v4, v30 offset:9032
	ds_write_b32 v4, v31 offset:9292
	ds_read_b32 v10, v2 offset:12672
	ds_read_b32 v11, v2 offset:12688
	ds_read_b32 v12, v2 offset:12704
	ds_read_b32 v13, v2 offset:12720
	ds_read_b32 v14, v3 offset:8512
	ds_read_b32 v15, v3 offset:9552
	ds_read_b32 v16, v3 offset:10592
	ds_read_b32 v17, v3 offset:11632
	s_waitcnt lgkmcnt(0)
	v_mfma_f32_16x16x4_f32 v[28:31], v10, v14, v[28:31]
	v_mfma_f32_16x16x4_f32 v[28:31], v11, v15, v[28:31]
	v_mfma_f32_16x16x4_f32 v[28:31], v12, v16, v[28:31]
	v_mfma_f32_16x16x4_f32 v[28:31], v13, v17, v[28:31]
	s_nop 9
	v_xor_b32_e32 v28, 0x80000000, v28
	v_xor_b32_e32 v29, 0x80000000, v29
	v_xor_b32_e32 v30, 0x80000000, v30
	v_xor_b32_e32 v31, 0x80000000, v31
	ds_write_b32 v4, v28 offset:8512
	ds_write_b32 v4, v29 offset:8772
	ds_write_b32 v4, v30 offset:9032
	ds_write_b32 v4, v31 offset:9292
	ds_read_b32 v10, v2 offset:8320
	ds_read_b32 v11, v2 offset:8336
	ds_read_b32 v12, v2 offset:8352
	ds_read_b32 v13, v2 offset:8368
	ds_read_b32 v14, v3 offset:0
	ds_read_b32 v15, v3 offset:1040
	ds_read_b32 v16, v3 offset:2080
	ds_read_b32 v17, v3 offset:3120
	s_waitcnt lgkmcnt(0)
	v_add_f32_e32 v14, v14, v5
	v_add_f32_e32 v15, v15, v6
	v_add_f32_e32 v16, v16, v7
	v_add_f32_e32 v17, v17, v8
	s_nop 1
	v_mfma_f32_16x16x4_f32 v[28:31], v10, v14, 0
	v_mfma_f32_16x16x4_f32 v[28:31], v11, v15, v[28:31]
	v_mfma_f32_16x16x4_f32 v[28:31], v12, v16, v[28:31]
	v_mfma_f32_16x16x4_f32 v[28:31], v13, v17, v[28:31]
	ds_read_b32 v10, v2 offset:8384
	ds_read_b32 v11, v2 offset:8400
	ds_read_b32 v12, v2 offset:8416
	ds_read_b32 v13, v2 offset:8432
	ds_read_b32 v14, v3 offset:64
	ds_read_b32 v15, v3 offset:1104
	ds_read_b32 v16, v3 offset:2144
	ds_read_b32 v17, v3 offset:3184
	s_waitcnt lgkmcnt(0)
	v_mfma_f32_16x16x4_f32 v[28:31], v10, v14, v[28:31]
	v_mfma_f32_16x16x4_f32 v[28:31], v11, v15, v[28:31]
	v_mfma_f32_16x16x4_f32 v[28:31], v12, v16, v[28:31]
	v_mfma_f32_16x16x4_f32 v[28:31], v13, v17, v[28:31]
	s_nop 9
	ds_write_b32 v4, v28 offset:128
	ds_write_b32 v4, v29 offset:388
	ds_write_b32 v4, v30 offset:648
	ds_write_b32 v4, v31 offset:908
	ds_read_b32 v10, v2 offset:8448
	ds_read_b32 v11, v2 offset:8464
	ds_read_b32 v12, v2 offset:8480
	ds_read_b32 v13, v2 offset:8496
	ds_read_b32 v14, v3 offset:128
	ds_read_b32 v15, v3 offset:1168
	ds_read_b32 v16, v3 offset:2208
	ds_read_b32 v17, v3 offset:3248
	s_waitcnt lgkmcnt(0)
; __device__ __forceinline__ void gdn_pre_phase(const Args& a, LAS unsigned char* lds, int slot) {
;     ...
; #pragma unroll 1
;             for (int lev = 1; lev < 4; ++lev)
; #pragma unroll 1
;                 for (int bb = 0; bb < 4 - lev; ++bb) {
;                     const int aa = bb + lev, q4 = quad * 4;
;                     float mv[4] = {0.f, 0.f, 0.f, 0.f};
;                     for (int cb = bb; cb < aa; ++cb) {
;                         for (int k = 0; k < 16; ++k) {
;                             float tk;
;                             if (cb == bb) tk = (cc < k) ? AT[(bb * 16 + k) * 65 + bb * 16 + cc] : (cc == k ? 1.f : 0.f);
;                             else tk = AT[(bb * 16 + k) * 65 + cb * 16 + cc];
; #pragma unroll
;                             for (int jj = 0; jj < 4; ++jj) mv[jj] += AT[(aa * 16 + q4 + jj) * 65 + cb * 16 + k] * tk;
;                         }
;                     }
;                     asm volatile("s_waitcnt lgkmcnt(0)" ::: "memory");
; #pragma unroll
;                     for (int jj = 0; jj < 4; ++jj) AT[(bb * 16 + q4 + jj) * 65 + aa * 16 + cc] = mv[jj];
;                     asm volatile("s_waitcnt lgkmcnt(0)" ::: "memory");
;                     float tv[4] = {mv[0], mv[1], mv[2], mv[3]};
;                     for (int k = 0; k < 16; ++k) {
;                         const float mk = AT[(bb * 16 + k) * 65 + aa * 16 + cc];
; #pragma unroll
;                         for (int jj = 0; jj < 4; ++jj) { const int ii = q4 + jj; const float dv = AT[(aa * 16 + ii) * 65 + aa * 16 + k]; if (k < ii) tv[jj] += dv * mk; }
;                     }
;                     asm volatile("s_waitcnt lgkmcnt(0)" ::: "memory");
; #pragma unroll
;                     for (int jj = 0; jj < 4; ++jj) AT[(bb * 16 + q4 + jj) * 65 + aa * 16 + cc] = -tv[jj];
;                     asm volatile("s_waitcnt lgkmcnt(0)" ::: "memory");
;                 }
	v_mfma_f32_16x16x4_f32 v[28:31], v10, v14, v[28:31]
	v_mfma_f32_16x16x4_f32 v[28:31], v11, v15, v[28:31]
	v_mfma_f32_16x16x4_f32 v[28:31], v12, v16, v[28:31]
	v_mfma_f32_16x16x4_f32 v[28:31], v13, v17, v[28:31]
	s_nop 9
	v_xor_b32_e32 v28, 0x80000000, v28
	v_xor_b32_e32 v29, 0x80000000, v29
	v_xor_b32_e32 v30, 0x80000000, v30
	v_xor_b32_e32 v31, 0x80000000, v31
	ds_write_b32 v4, v28 offset:128
	ds_write_b32 v4, v29 offset:388
	ds_write_b32 v4, v30 offset:648
	ds_write_b32 v4, v31 offset:908
	ds_read_b32 v10, v2 offset:12544
	ds_read_b32 v11, v2 offset:12560
	ds_read_b32 v12, v2 offset:12576
	ds_read_b32 v13, v2 offset:12592
	ds_read_b32 v14, v3 offset:4224
	ds_read_b32 v15, v3 offset:5264
	ds_read_b32 v16, v3 offset:6304
	ds_read_b32 v17, v3 offset:7344
	s_waitcnt lgkmcnt(0)
	v_add_f32_e32 v14, v14, v5
	v_add_f32_e32 v15, v15, v6
	v_add_f32_e32 v16, v16, v7
	v_add_f32_e32 v17, v17, v8
	s_nop 1
	v_mfma_f32_16x16x4_f32 v[28:31], v10, v14, 0
	v_mfma_f32_16x16x4_f32 v[28:31], v11, v15, v[28:31]
	v_mfma_f32_16x16x4_f32 v[28:31], v12, v16, v[28:31]
	v_mfma_f32_16x16x4_f32 v[28:31], v13, v17, v[28:31]
	ds_read_b32 v10, v2 offset:12608
	ds_read_b32 v11, v2 offset:12624
	ds_read_b32 v12, v2 offset:12640
	ds_read_b32 v13, v2 offset:12656
	ds_read_b32 v14, v3 offset:4288
	ds_read_b32 v15, v3 offset:5328
	ds_read_b32 v16, v3 offset:6368
	ds_read_b32 v17, v3 offset:7408
	s_waitcnt lgkmcnt(0)
	v_mfma_f32_16x16x4_f32 v[28:31], v10, v14, v[28:31]
	v_mfma_f32_16x16x4_f32 v[28:31], v11, v15, v[28:31]
	v_mfma_f32_16x16x4_f32 v[28:31], v12, v16, v[28:31]
	v_mfma_f32_16x16x4_f32 v[28:31], v13, v17, v[28:31]
	s_nop 9
	ds_write_b32 v4, v28 offset:4352
	ds_write_b32 v4, v29 offset:4612
	ds_write_b32 v4, v30 offset:4872
	ds_write_b32 v4, v31 offset:5132
	ds_read_b32 v10, v2 offset:12672
	ds_read_b32 v11, v2 offset:12688
	ds_read_b32 v12, v2 offset:12704
	ds_read_b32 v13, v2 offset:12720
	ds_read_b32 v14, v3 offset:4352
	ds_read_b32 v15, v3 offset:5392
	ds_read_b32 v16, v3 offset:6432
	ds_read_b32 v17, v3 offset:7472
	s_waitcnt lgkmcnt(0)
	v_mfma_f32_16x16x4_f32 v[28:31], v10, v14, v[28:31]
	v_mfma_f32_16x16x4_f32 v[28:31], v11, v15, v[28:31]
	v_mfma_f32_16x16x4_f32 v[28:31], v12, v16, v[28:31]
	v_mfma_f32_16x16x4_f32 v[28:31], v13, v17, v[28:31]
	s_nop 9
	v_xor_b32_e32 v28, 0x80000000, v28
	v_xor_b32_e32 v29, 0x80000000, v29
	v_xor_b32_e32 v30, 0x80000000, v30
	v_xor_b32_e32 v31, 0x80000000, v31
	ds_write_b32 v4, v28 offset:4352
	ds_write_b32 v4, v29 offset:4612
	ds_write_b32 v4, v30 offset:4872
	ds_write_b32 v4, v31 offset:5132
	ds_read_b32 v10, v2 offset:12480
	ds_read_b32 v11, v2 offset:12496
	ds_read_b32 v12, v2 offset:12512
	ds_read_b32 v13, v2 offset:12528
	ds_read_b32 v14, v3 offset:0
	ds_read_b32 v15, v3 offset:1040
	ds_read_b32 v16, v3 offset:2080
	ds_read_b32 v17, v3 offset:3120
	s_waitcnt lgkmcnt(0)
	v_add_f32_e32 v14, v14, v5
	v_add_f32_e32 v15, v15, v6
	v_add_f32_e32 v16, v16, v7
	v_add_f32_e32 v17, v17, v8
	s_nop 1
	v_mfma_f32_16x16x4_f32 v[28:31], v10, v14, 0
	v_mfma_f32_16x16x4_f32 v[28:31], v11, v15, v[28:31]
	v_mfma_f32_16x16x4_f32 v[28:31], v12, v16, v[28:31]
	v_mfma_f32_16x16x4_f32 v[28:31], v13, v17, v[28:31]
	ds_read_b32 v10, v2 offset:12544
	ds_read_b32 v11, v2 offset:12560
	ds_read_b32 v12, v2 offset:12576
	ds_read_b32 v13, v2 offset:12592
	ds_read_b32 v14, v3 offset:64
	ds_read_b32 v15, v3 offset:1104
	ds_read_b32 v16, v3 offset:2144
	ds_read_b32 v17, v3 offset:3184
	s_waitcnt lgkmcnt(0)
	v_mfma_f32_16x16x4_f32 v[28:31], v10, v14, v[28:31]
	v_mfma_f32_16x16x4_f32 v[28:31], v11, v15, v[28:31]
	v_mfma_f32_16x16x4_f32 v[28:31], v12, v16, v[28:31]
	v_mfma_f32_16x16x4_f32 v[28:31], v13, v17, v[28:31]
	ds_read_b32 v10, v2 offset:12608
	ds_read_b32 v11, v2 offset:12624
	ds_read_b32 v12, v2 offset:12640
	ds_read_b32 v13, v2 offset:12656
	ds_read_b32 v14, v3 offset:128
	ds_read_b32 v15, v3 offset:1168
	ds_read_b32 v16, v3 offset:2208
	ds_read_b32 v17, v3 offset:3248
	s_waitcnt lgkmcnt(0)
	v_mfma_f32_16x16x4_f32 v[28:31], v10, v14, v[28:31]
	v_mfma_f32_16x16x4_f32 v[28:31], v11, v15, v[28:31]
	v_mfma_f32_16x16x4_f32 v[28:31], v12, v16, v[28:31]
	v_mfma_f32_16x16x4_f32 v[28:31], v13, v17, v[28:31]
	s_nop 9
	ds_write_b32 v4, v28 offset:192
	ds_write_b32 v4, v29 offset:452
	ds_write_b32 v4, v30 offset:712
	ds_write_b32 v4, v31 offset:972
	ds_read_b32 v10, v2 offset:12672
	ds_read_b32 v11, v2 offset:12688
	ds_read_b32 v12, v2 offset:12704
	ds_read_b32 v13, v2 offset:12720
	ds_read_b32 v14, v3 offset:192
	ds_read_b32 v15, v3 offset:1232
	ds_read_b32 v16, v3 offset:2272
	ds_read_b32 v17, v3 offset:3312
	s_waitcnt lgkmcnt(0)
	v_mfma_f32_16x16x4_f32 v[28:31], v10, v14, v[28:31]
	v_mfma_f32_16x16x4_f32 v[28:31], v11, v15, v[28:31]
	v_mfma_f32_16x16x4_f32 v[28:31], v12, v16, v[28:31]
	v_mfma_f32_16x16x4_f32 v[28:31], v13, v17, v[28:31]
	s_nop 9
	v_xor_b32_e32 v28, 0x80000000, v28
	v_xor_b32_e32 v29, 0x80000000, v29
	v_xor_b32_e32 v30, 0x80000000, v30
	v_xor_b32_e32 v31, 0x80000000, v31
	ds_write_b32 v4, v28 offset:192
	ds_write_b32 v4, v29 offset:452
	ds_write_b32 v4, v30 offset:712
	ds_write_b32 v4, v31 offset:972
	s_waitcnt lgkmcnt(0)
